# MLA unit: next-item L2-touch loads issued at the start of the last tile step into dedicated VGPRs; post-loop barriers no longer wait on vmcnt
# speedup vs baseline: 1.0231x; 1.0091x over previous
.LBB0_514:
	v_mov_b32_e32 v249, 0
	v_mov_b32_e32 v250, v186
	s_mov_b32 s101, 0
	s_cmpk_gt_i32 s65, 0x1ff
	s_cbranch_scc1 .Lmpf_541
	s_cmpk_gt_i32 s65, 0x7f
	s_mov_b64 s[54:55], -1
	s_cbranch_scc0 .Lmpf_533
	s_add_i32 s54, s65, 0xff80
	s_and_b32 s100, s54, 0xffff
	s_mul_i32 s100, s100, 0xaaab
	s_lshr_b32 s100, s100, 21
	s_mul_i32 s55, s100, 48
	s_sub_i32 s54, s54, s55
	s_and_b32 s58, s54, 0xffff
	s_mov_b64 s[54:55], 0
	s_cmp_lt_u32 s58, 16
	s_mov_b32 s56, 0
	s_cbranch_scc1 .Lmpf_528
	s_cmp_gt_u32 s58, 31
	s_mov_b64 s[54:55], -1
	s_cbranch_scc0 .Lmpf_525
	s_sub_i32 s56, s58, 32
	s_mov_b64 s[54:55], 0

.Lmpf_528:
	s_lshl_b32 s57, s58, 2
	s_add_i32 s55, s57, -2
	s_cmp_lg_u32 s58, 0
	s_cselect_b32 s55, s55, 0
	s_sub_i32 s57, s57, s55
	s_lshl_b32 s57, s57, 6
	s_and_b32 s100, 0xffff, s100
	s_addk_i32 s57, 0x100
	s_lshl_b32 s100, s100, 12
	s_add_i32 s100, s100, s56
	v_cmp_gt_i32_e32 vcc, s57, v250
	s_and_saveexec_b64 s[56:57], vcc
	s_cbranch_execz .Lmpf_530
	v_lshl_add_u32 v244, s55, 6, v250
	v_ashrrev_i32_e32 v245, 31, v244
	v_lshlrev_b64 v[244:245], s54, v[244:245]
	v_lshl_add_u64 v[244:245], v[244:245], 0, s[100:101]
	v_mov_b64_e32 v[246:247], s[40:41]
	v_mad_u64_u32 v[246:247], s[60:61], v244, s66, v[246:247]
	v_mad_i32_i24 v247, v245, s66, v247
	global_load_dword v240, v[246:247], off offset:1024
	global_load_dword v241, v[246:247], off offset:2048
.Lmpf_530:
	s_or_b64 exec, exec, s[56:57]
	v_cmp_lt_i32_e32 vcc, s68, v250
	s_and_saveexec_b64 s[56:57], vcc
	s_cbranch_execz .Lmpf_532
	v_lshl_add_u32 v248, s58, 8, v250
	v_add_u32_e32 v248, 0xffffff00, v248
	v_lshlrev_b64 v[244:245], s54, v[248:249]
	v_lshl_add_u64 v[244:245], v[244:245], 0, s[100:101]
	v_mov_b64_e32 v[246:247], s[40:41]
	v_mad_u64_u32 v[246:247], s[54:55], v244, s66, v[246:247]
	v_mad_u32_u24 v247, v245, s66, v247
	global_load_dword v242, v[246:247], off

.Lmpf_533:
	s_and_b64 vcc, exec, s[54:55]
	s_cbranch_vccz .Lmpf_541
	s_ashr_i32 s54, s65, 4
	s_ashr_i32 s55, s54, 31
	s_lshl_b64 s[54:55], s[54:55], 12
	v_cmp_lt_i32_e32 vcc, s69, v250
	s_and_saveexec_b64 s[56:57], vcc
	s_xor_b64 s[56:57], exec, s[56:57]
	s_cbranch_execz .Lmpf_538
	v_cmp_gt_u32_e32 vcc, s70, v250
	s_and_saveexec_b64 s[58:59], vcc
	s_cbranch_execz .Lmpf_537
	s_not_b32 s100, s65
	s_lshl_b32 s100, s100, 8
	s_and_b32 s100, s100, 0xf00
	v_add_u32_e32 v248, 0xffffff40, v250
	s_or_b32 s60, s54, s100
	s_mov_b32 s61, s55
	v_lshl_add_u64 v[244:245], s[60:61], 0, v[248:249]
	v_mov_b64_e32 v[246:247], s[12:13]
	v_mad_u64_u32 v[246:247], s[60:61], v244, s71, v[246:247]
	v_mad_i32_i24 v247, v245, s71, v247
	global_load_dword v240, v[246:247], off
	global_load_dword v241, v[246:247], off offset:128

.Lmpf_538:
	s_or_saveexec_b64 s[56:57], s[56:57]
	s_xor_b64 exec, exec, s[56:57]
	s_cbranch_execz .Lmpf_540
	v_ashrrev_i32_e32 v251, 31, v250
	v_lshl_add_u64 v[244:245], s[54:55], 0, v[250:251]
	v_mov_b64_e32 v[252:253], s[16:17]
	v_lshlrev_b64 v[246:247], 11, v[244:245]
	v_mad_u64_u32 v[252:253], s[54:55], v244, s66, v[252:253]
	v_lshl_add_u64 v[246:247], s[44:45], 0, v[246:247]
	v_mad_i32_i24 v248, v245, s66, v253
	v_add_co_u32_e32 v244, vcc, 0x1000, v252
	s_nop 1
	v_addc_co_u32_e32 v245, vcc, 0, v248, vcc
	global_load_dword v240, v[246:247], off
	global_load_dword v241, v[246:247], off offset:128
	global_load_dword v242, v[244:245], off offset:768
.Lmpf_540:
	s_or_b64 exec, exec, s[56:57]
.Lmpf_541:
	s_add_i32 s54, s95, 2
	s_add_i32 s95, s95, 1
	s_mul_hi_u32 s55, s95, 0xaaaaaaab
	s_lshr_b32 s55, s55, 2
	v_or_b32_e32 v82, v182, v188
	s_mul_i32 s55, s55, 6
	v_add_u32_e32 v0, 0, v187
	v_lshlrev_b32_e32 v82, 6, v82
	s_sub_i32 s55, s95, s55
	v_add3_u32 v106, v0, v179, v82
	s_mulk_i32 s55, 0x5000
	v_add_u32_e32 v0, s55, v106
	s_mul_hi_u32 s55, s54, 0xaaaaaaab
	s_lshr_b32 s55, s55, 2
	s_mul_i32 s55, s55, 6
	s_sub_i32 s55, s54, s55
	s_mulk_i32 s55, 0x5000
	v_or_b32_e32 v82, s55, v185
	v_add_u32_e32 v83, 0, v82
	ds_read_b128 v[100:103], v83
	ds_read_b128 v[108:111], v83 offset:4096
	v_xad_u32 v83, v82, 32, 0
	ds_read_b128 v[138:141], v83
	ds_read_b128 v[142:145], v83 offset:4096
	v_add_u32_e32 v0, 0x3000, v0
	v_add_f32_e32 v83, v66, v67
	v_xad_u32 v82, v82, 64, 0
	ds_read_b128 v[146:149], v82
	ds_read_b128 v[150:153], v82 offset:4096
	v_add_f32_e32 v82, v68, v83
	v_add_f32_e32 v82, v69, v82
	v_add_f32_e32 v82, v70, v82
	v_add_f32_e32 v107, v71, v82
	s_waitcnt lgkmcnt(5)
	v_mfma_f32_32x32x16_bf16 v[82:97], v[100:103], v[134:137], v[34:49]
	v_cvt_pk_bf16_f32 v98, v66, v67
	v_cvt_pk_bf16_f32 v99, v68, v69
	v_bitop3_b32 v66, s55, v176, v185 bitop3:0x36
	v_add_u32_e32 v66, 0, v66
	ds_read_b128 v[102:105], v66
	ds_read_b128 v[154:157], v66 offset:4096
	s_waitcnt lgkmcnt(6)
	v_mfma_f32_32x32x16_bf16 v[34:49], v[108:111], v[134:137], v[34:49]
	v_add_f32_e32 v66, v72, v107
	v_add_f32_e32 v66, v73, v66
	v_add_f32_e32 v66, v74, v66
	v_add_f32_e32 v66, v75, v66
	v_cvt_pk_bf16_f32 v100, v70, v71
	v_cvt_pk_bf16_f32 v101, v72, v73
	s_waitcnt lgkmcnt(5)
	v_mfma_f32_32x32x16_bf16 v[82:97], v[138:141], v[130:133], v[82:97]
	v_add_f32_e32 v66, v76, v66
	v_add_f32_e32 v66, v77, v66
	v_add_f32_e32 v66, v78, v66
	v_add_f32_e32 v66, v79, v66
	v_cvt_pk_bf16_f32 v74, v74, v75
	v_cvt_pk_bf16_f32 v75, v76, v77
	s_waitcnt lgkmcnt(4)
	v_mfma_f32_32x32x16_bf16 v[34:49], v[142:145], v[130:133], v[34:49]
	v_add_f32_e32 v66, v80, v66
	v_add_f32_e32 v66, v81, v66
	v_add_f32_e32 v66, v50, v66
	v_add_f32_e32 v66, v51, v66
	v_cvt_pk_bf16_f32 v76, v78, v79
	v_cvt_pk_bf16_f32 v77, v80, v81
	v_add_u32_e32 v67, s55, v184
	ds_read_b128 v[78:81], v67 offset:8192
	ds_read_b128 v[108:111], v67 offset:10240
	v_or_b32_e32 v67, s55, v183
	v_add_u32_e32 v67, 0x2000, v67
	s_waitcnt lgkmcnt(5)
	v_mfma_f32_32x32x16_bf16 v[82:97], v[146:149], v[126:129], v[82:97]
	v_add_f32_e32 v66, v52, v66
	v_add_f32_e32 v66, v53, v66
	v_add_f32_e32 v66, v54, v66
	v_add_f32_e32 v66, v55, v66
	v_cvt_pk_bf16_f32 v70, v50, v51
	v_cvt_pk_bf16_f32 v71, v52, v53
	s_waitcnt lgkmcnt(4)
	v_mfma_f32_32x32x16_bf16 v[34:49], v[150:153], v[126:129], v[34:49]
	v_add_f32_e32 v50, v56, v66
	v_add_f32_e32 v50, v57, v50
	v_add_f32_e32 v50, v58, v50
	v_add_f32_e32 v50, v59, v50
	v_cvt_pk_bf16_f32 v72, v54, v55
	v_cvt_pk_bf16_f32 v73, v56, v57
	v_xad_u32 v51, v67, 32, 0
	ds_read_b128 v[52:55], v51
	ds_read_b128 v[126:129], v51 offset:2048
	s_waitcnt lgkmcnt(5)
	v_mfma_f32_32x32x16_bf16 v[82:97], v[102:105], v[122:125], v[82:97]
	v_add_f32_e32 v50, v60, v50
	v_add_f32_e32 v50, v61, v50
	v_add_f32_e32 v50, v62, v50
	v_add_f32_e32 v50, v63, v50
	v_cvt_pk_bf16_f32 v66, v58, v59
	v_cvt_pk_bf16_f32 v67, v60, v61
	s_waitcnt lgkmcnt(4)
	v_mfma_f32_32x32x16_bf16 v[34:49], v[154:157], v[122:125], v[34:49]
	v_add_f32_e32 v50, v64, v50
	v_add_f32_e32 v50, v65, v50
	v_add_f32_e32 v50, 0, v50
	v_cvt_pk_bf16_f32 v68, v62, v63
	v_cvt_pk_bf16_f32 v69, v64, v65
	s_waitcnt lgkmcnt(3)
	v_mfma_f32_32x32x16_bf16 v[82:97], v[78:81], v[118:121], v[82:97]
	s_waitcnt lgkmcnt(2)
	v_mfma_f32_32x32x16_bf16 v[34:49], v[108:111], v[118:121], v[34:49]
	s_waitcnt lgkmcnt(1)
	v_mfma_f32_32x32x16_bf16 v[82:97], v[52:55], v[114:117], v[82:97]
	s_waitcnt lgkmcnt(0)
	v_mfma_f32_32x32x16_bf16 v[34:49], v[126:129], v[114:117], v[34:49]
	ds_read_b64_tr_b16 v[102:103], v0 offset:0
	ds_read_b64_tr_b16 v[104:105], v0 offset:512
	ds_read_b64_tr_b16 v[78:79], v0 offset:4096
	ds_read_b64_tr_b16 v[80:81], v0 offset:4608
	s_lshl_b32 s54, s54, 6
	s_or_b32 s55, s54, 63
	s_cmp_le_i32 s55, s10
	s_cbranch_scc1 .LBB0_516
	v_or_b32_e32 v51, s54, v182
	v_or_b32_e32 v52, 32, v51
	v_cmp_le_i32_e32 vcc, v52, v172
	v_or_b32_e32 v52, 33, v51
	s_nop 3
	v_cndmask_b32_e32 v34, v177, v34, vcc
	v_cmp_lt_i32_e32 vcc, v51, v172
	s_nop 1
	v_cndmask_b32_e32 v83, v177, v83, vcc
	v_cmp_le_i32_e32 vcc, v51, v172
	s_nop 1
	v_cndmask_b32_e32 v82, v177, v82, vcc
	v_cmp_le_i32_e32 vcc, v52, v172
	v_or_b32_e32 v52, 2, v51
	s_nop 0
	v_cndmask_b32_e32 v35, v177, v35, vcc
	v_cmp_le_i32_e32 vcc, v52, v172
	v_or_b32_e32 v52, 34, v51
	s_nop 0
	v_cndmask_b32_e32 v84, v177, v84, vcc
	v_cmp_le_i32_e32 vcc, v52, v172
	v_or_b32_e32 v52, 3, v51
	s_nop 0
	v_cndmask_b32_e32 v36, v177, v36, vcc
	v_cmp_le_i32_e32 vcc, v52, v172
	v_or_b32_e32 v52, 35, v51
	s_nop 0
	v_cndmask_b32_e32 v85, v177, v85, vcc
	v_cmp_le_i32_e32 vcc, v52, v172
	v_or_b32_e32 v52, 8, v51
	s_nop 0
	v_cndmask_b32_e32 v37, v177, v37, vcc
	v_cmp_le_i32_e32 vcc, v52, v172
	v_or_b32_e32 v52, 40, v51
	s_nop 0
	v_cndmask_b32_e32 v86, v177, v86, vcc
	v_cmp_le_i32_e32 vcc, v52, v172
	v_or_b32_e32 v52, 9, v51
	s_nop 0
	v_cndmask_b32_e32 v38, v177, v38, vcc
	v_cmp_le_i32_e32 vcc, v52, v172
	v_or_b32_e32 v52, 41, v51
	s_nop 0
	v_cndmask_b32_e32 v87, v177, v87, vcc
	v_cmp_le_i32_e32 vcc, v52, v172
	v_or_b32_e32 v52, 10, v51
	s_nop 0
	v_cndmask_b32_e32 v39, v177, v39, vcc
	v_cmp_le_i32_e32 vcc, v52, v172
	v_or_b32_e32 v52, 42, v51
	s_nop 0
	v_cndmask_b32_e32 v88, v177, v88, vcc
	v_cmp_le_i32_e32 vcc, v52, v172
	v_or_b32_e32 v52, 11, v51
	s_nop 0
	v_cndmask_b32_e32 v40, v177, v40, vcc
	v_cmp_le_i32_e32 vcc, v52, v172
	v_or_b32_e32 v52, 43, v51
	s_nop 0
	v_cndmask_b32_e32 v89, v177, v89, vcc
	v_cmp_le_i32_e32 vcc, v52, v172
	v_or_b32_e32 v52, 16, v51
	s_nop 0
	v_cndmask_b32_e32 v41, v177, v41, vcc
	v_cmp_le_i32_e32 vcc, v52, v172
	v_or_b32_e32 v52, 48, v51
	s_nop 0
	v_cndmask_b32_e32 v90, v177, v90, vcc
	v_cmp_le_i32_e32 vcc, v52, v172
	v_or_b32_e32 v52, 17, v51
	s_nop 0
	v_cndmask_b32_e32 v42, v177, v42, vcc
	v_cmp_le_i32_e32 vcc, v52, v172
	v_or_b32_e32 v52, 49, v51
	s_nop 0
	v_cndmask_b32_e32 v91, v177, v91, vcc
	v_cmp_le_i32_e32 vcc, v52, v172
	v_or_b32_e32 v52, 18, v51
	s_nop 0
	v_cndmask_b32_e32 v43, v177, v43, vcc
	v_cmp_le_i32_e32 vcc, v52, v172
	v_or_b32_e32 v52, 50, v51
	s_nop 0
	v_cndmask_b32_e32 v92, v177, v92, vcc
	v_cmp_le_i32_e32 vcc, v52, v172
	v_or_b32_e32 v52, 19, v51
	s_nop 0
	v_cndmask_b32_e32 v44, v177, v44, vcc
	v_cmp_le_i32_e32 vcc, v52, v172
	v_or_b32_e32 v52, 51, v51
	s_nop 0
	v_cndmask_b32_e32 v93, v177, v93, vcc
	v_cmp_le_i32_e32 vcc, v52, v172
	v_or_b32_e32 v52, 24, v51
	s_nop 0
	v_cndmask_b32_e32 v45, v177, v45, vcc
	v_cmp_le_i32_e32 vcc, v52, v172
	v_or_b32_e32 v52, 56, v51
	s_nop 0
	v_cndmask_b32_e32 v94, v177, v94, vcc
	v_cmp_le_i32_e32 vcc, v52, v172
	v_or_b32_e32 v52, 25, v51
	s_nop 0
	v_cndmask_b32_e32 v46, v177, v46, vcc
	v_cmp_le_i32_e32 vcc, v52, v172
	v_or_b32_e32 v52, 57, v51
	s_nop 0
	v_cndmask_b32_e32 v95, v177, v95, vcc
	v_cmp_le_i32_e32 vcc, v52, v172
	v_or_b32_e32 v52, 26, v51
	s_nop 0
	v_cndmask_b32_e32 v47, v177, v47, vcc
	v_cmp_le_i32_e32 vcc, v52, v172
	v_or_b32_e32 v52, 58, v51
	s_nop 0
	v_cndmask_b32_e32 v96, v177, v96, vcc
	v_cmp_le_i32_e32 vcc, v52, v172
	v_or_b32_e32 v52, 27, v51
	v_or_b32_e32 v51, 59, v51
	v_cndmask_b32_e32 v48, v177, v48, vcc
	v_cmp_le_i32_e32 vcc, v52, v172
	s_nop 1
	v_cndmask_b32_e32 v97, v177, v97, vcc
	v_cmp_le_i32_e32 vcc, v51, v172
	s_nop 1
	v_cndmask_b32_e32 v49, v177, v49, vcc

.LBB0_520:
	s_waitcnt lgkmcnt(0)
	s_barrier
.LBB0_541:
	s_or_b32 s10, s78, 3
	s_mul_hi_u32 s54, s10, 0x2aaaaaab
	s_mul_i32 s54, s54, 6
	s_sub_i32 s10, s10, s54
	s_mulk_i32 s10, 0x5000
	v_add_u32_e32 v0, s10, v106
	ds_read_b64_tr_b16 v[58:59], v0 offset:12288
	ds_read_b64_tr_b16 v[60:61], v0 offset:12800
	ds_read_b64_tr_b16 v[62:63], v0 offset:13312
	ds_read_b64_tr_b16 v[64:65], v0 offset:13824
	ds_read_b64_tr_b16 v[66:67], v0 offset:14336
	ds_read_b64_tr_b16 v[68:69], v0 offset:14848
	ds_read_b64_tr_b16 v[70:71], v0 offset:15360
	ds_read_b64_tr_b16 v[72:73], v0 offset:15872
	ds_read_b64_tr_b16 v[74:75], v0 offset:16384
	ds_read_b64_tr_b16 v[76:77], v0 offset:16896
	ds_read_b64_tr_b16 v[78:79], v0 offset:17408
	ds_read_b64_tr_b16 v[80:81], v0 offset:17920
	ds_read_b64_tr_b16 v[98:99], v0 offset:18432
	ds_read_b64_tr_b16 v[100:101], v0 offset:18944
	ds_read_b64_tr_b16 v[102:103], v0 offset:19456
	ds_read_b64_tr_b16 v[104:105], v0 offset:19968
	v_mov_b32_e32 v0, v186
	s_waitcnt lgkmcnt(0)
	s_barrier
	v_mov_b32_e32 v53, s53
	v_ashrrev_i32_e32 v50, 1, v0
	v_and_b32_e32 v50, 0xffffffe0, v50
	v_and_or_b32 v52, v0, 31, s19
	v_ashrrev_i32_e32 v51, 31, v50
	v_or_b32_e32 v52, s52, v52
	v_lshl_add_u64 v[50:51], v[52:53], 0, v[50:51]
	v_mov_b64_e32 v[52:53], s[16:17]
	v_mad_u64_u32 v[52:53], s[52:53], v50, s66, v[52:53]
	v_mad_i32_i24 v53, v51, s66, v53
	s_mov_b32 s19, s11
	v_lshrrev_b32_e32 v0, 2, v0
	v_lshl_add_u64 v[52:53], v[52:53], 0, s[18:19]
	v_and_b32_e32 v0, 8, v0
	v_lshl_add_u64 v[112:113], v[52:53], 0, v[0:1]
	s_movk_i32 s10, 0x1000
	v_add_co_u32_e32 v52, vcc, s10, v112
	v_cvt_pk_bf16_f32 v108, v82, v83
	s_nop 0
	v_addc_co_u32_e32 v53, vcc, 0, v113, vcc
	global_load_dwordx2 v[52:53], v[52:53], off offset:832
	v_cvt_pk_bf16_f32 v109, v84, v85
	v_cvt_pk_bf16_f32 v110, v86, v87
	v_cvt_pk_bf16_f32 v111, v88, v89
	v_add_f32_e32 v57, v82, v34
	v_add_f32_e32 v82, v83, v35
	s_waitcnt lgkmcnt(14)
	v_mfma_f32_32x32x16_bf16 v[18:33], v[58:61], v[108:111], v[18:33]
	v_add_f32_e32 v83, v84, v36
	v_add_f32_e32 v84, v85, v37
	v_add_f32_e32 v85, v86, v38
	v_cvt_pk_bf16_f32 v34, v34, v35
	v_cvt_pk_bf16_f32 v35, v36, v37
	v_cvt_pk_bf16_f32 v36, v38, v39
	v_add_f32_e32 v38, 0, v57
	s_waitcnt lgkmcnt(6)
	v_mfma_f32_32x32x16_bf16 v[2:17], v[74:77], v[108:111], v[2:17]
	v_cvt_pk_bf16_f32 v58, v90, v91
	v_cvt_pk_bf16_f32 v59, v92, v93
	v_cvt_pk_bf16_f32 v60, v94, v95
	v_cvt_pk_bf16_f32 v61, v96, v97
	v_add_f32_e32 v38, v82, v38
	v_add_f32_e32 v38, v83, v38
	v_add_f32_e32 v38, v84, v38
	v_mfma_f32_32x32x16_bf16 v[18:33], v[62:65], v[58:61], v[18:33]
	v_add_f32_e32 v86, v87, v39
	v_add_f32_e32 v38, v85, v38
	v_add_f32_e32 v87, v88, v40
	v_add_f32_e32 v38, v86, v38
	v_add_f32_e32 v88, v89, v41
	v_add_f32_e32 v38, v87, v38
	v_add_f32_e32 v74, v90, v42
	s_waitcnt lgkmcnt(4)
	v_mfma_f32_32x32x16_bf16 v[2:17], v[78:81], v[58:61], v[2:17]
	v_add_f32_e32 v38, v88, v38
	v_add_f32_e32 v75, v91, v43
	v_add_f32_e32 v38, v74, v38
	v_add_f32_e32 v76, v92, v44
	v_cvt_pk_bf16_f32 v37, v40, v41
	v_add_f32_e32 v38, v75, v38
	v_add_f32_e32 v77, v93, v45
	v_mfma_f32_32x32x16_bf16 v[18:33], v[66:69], v[34:37], v[18:33]
	v_add_f32_e64 v62, v94, v46
	v_add_f32_e64 v63, v95, v47
	v_add_f32_e64 v64, v96, v48
	v_add_f32_e64 v65, v97, v49
	v_cvt_pk_bf16_f32 v41, v44, v45
	v_cvt_pk_bf16_f32 v40, v42, v43
	v_cvt_pk_bf16_f32 v42, v46, v47
	v_cvt_pk_bf16_f32 v43, v48, v49
	s_waitcnt vmcnt(0)
	v_lshlrev_b32_e32 v57, 16, v52
	s_waitcnt lgkmcnt(2)
	v_mfma_f32_32x32x16_bf16 v[2:17], v[98:101], v[34:37], v[2:17]
	v_add_f32_e32 v34, v76, v38
	v_add_f32_e32 v34, v77, v34
	v_add_f32_e32 v34, v62, v34
	v_add_f32_e32 v34, v63, v34
	v_add_f32_e32 v34, v64, v34
	v_add_f32_e32 v34, v65, v34
	v_add_f32_e32 v34, v107, v34
	v_mov_b32_e32 v35, v34
	s_nop 1
	v_permlane32_swap_b32_e32 v34, v35
	v_add_f32_e32 v38, v34, v35
	v_div_scale_f32 v34, s[52:53], v38, v38, 1.0
	v_rcp_f32_e32 v39, v34
	s_mov_b64 s[52:53], 0x1340
	v_and_b32_e32 v52, 0xffff0000, v52
	v_mul_f32_e32 v48, 0xbfb8aa3b, v57
	v_fma_f32 v35, -v34, v39, 1.0
	v_fmac_f32_e32 v39, v35, v39
	v_div_scale_f32 v35, vcc, 1.0, v38, 1.0
	v_mul_f32_e32 v44, v35, v39
	v_fma_f32 v36, -v34, v44, v35
	v_fmac_f32_e32 v44, v36, v39
	v_fma_f32 v45, -v34, v44, v35
	v_lshl_add_u64 v[34:35], v[112:113], 0, s[52:53]
	v_mul_f32_e32 v49, 0xbfb8aa3b, v52
	v_mfma_f32_32x32x16_bf16 v[18:33], v[70:73], v[40:43], v[18:33]
	v_exp_f32_e32 v48, v48
	v_exp_f32_e32 v49, v49
	v_div_fmas_f32 v39, v45, v39, v44
	v_div_fixup_f32 v38, v39, v38, 1.0
	v_pk_add_f32 v[44:45], v[48:49], 1.0 op_sel_hi:[1,0]
	s_nop 0
	v_div_scale_f32 v39, s[52:53], v45, v45, v52
	s_waitcnt lgkmcnt(0)
	v_mfma_f32_32x32x16_bf16 v[2:17], v[102:105], v[40:43], v[2:17]
	global_load_dwordx2 v[36:37], v[34:35], off offset:80
	global_load_dwordx2 v[40:41], v[34:35], off offset:96
	global_load_dwordx2 v[42:43], v[34:35], off offset:112
	global_load_dwordx2 v[46:47], v[34:35], off offset:16
	v_rcp_f32_e32 v58, v39
	v_lshlrev_b64 v[48:49], 11, v[50:51]
	v_pk_mul_f32 v[18:19], v[18:19], v[38:39] op_sel_hi:[1,0]
	v_lshl_add_u64 v[48:49], s[48:49], 0, v[48:49]
	v_fma_f32 v50, -v39, v58, 1.0
	v_fmac_f32_e32 v58, v50, v58
	v_div_scale_f32 v50, vcc, v52, v45, v52
	v_mul_f32_e32 v51, v50, v58
	v_fma_f32 v59, -v39, v51, v50
	v_fmac_f32_e32 v51, v59, v58
	v_div_scale_f32 v59, s[52:53], v44, v44, v57
	v_rcp_f32_e32 v60, v59
	v_fma_f32 v39, -v39, v51, v50
	v_div_fmas_f32 v39, v39, v58, v51
	v_div_fixup_f32 v45, v39, v45, v52
	v_fma_f32 v39, -v59, v60, 1.0
	v_fmac_f32_e32 v60, v39, v60
	v_div_scale_f32 v39, vcc, v57, v44, v57
	v_mul_f32_e32 v52, v39, v60
	v_fma_f32 v50, -v59, v52, v39
	v_lshlrev_b32_e32 v58, 16, v53
	v_and_b32_e32 v53, 0xffff0000, v53
	v_fmac_f32_e32 v52, v50, v60
	v_mul_f32_e32 v50, 0xbfb8aa3b, v58
	v_mul_f32_e32 v51, 0xbfb8aa3b, v53
	v_exp_f32_e32 v50, v50
	v_exp_f32_e32 v51, v51
	v_fma_f32 v39, -v59, v52, v39
	v_div_fmas_f32 v39, v39, v60, v52
	v_div_fixup_f32 v44, v39, v44, v57
	v_pk_add_f32 v[50:51], v[50:51], 1.0 op_sel_hi:[1,0]
	v_pk_mul_f32 v[20:21], v[20:21], v[38:39] op_sel_hi:[1,0]
	v_div_scale_f32 v52, s[52:53], v51, v51, v53
	v_rcp_f32_e32 v59, v52
	v_pk_mul_f32 v[18:19], v[18:19], v[44:45]
	v_fma_f32 v39, -v52, v59, 1.0
	v_fmac_f32_e32 v59, v39, v59
	v_div_scale_f32 v39, vcc, v53, v51, v53
	v_mul_f32_e32 v44, v39, v59
	v_fma_f32 v45, -v52, v44, v39
	v_fmac_f32_e32 v44, v45, v59
	v_fma_f32 v39, -v52, v44, v39
	v_div_scale_f32 v52, s[52:53], v50, v50, v58
	v_rcp_f32_e32 v57, v52
	v_div_fmas_f32 v39, v39, v59, v44
	v_div_fixup_f32 v45, v39, v51, v53
	v_fma_f32 v39, -v52, v57, 1.0
	v_fmac_f32_e32 v57, v39, v57
	v_div_scale_f32 v39, vcc, v58, v50, v58
	v_mul_f32_e32 v44, v39, v57
	v_fma_f32 v51, -v52, v44, v39
	v_fmac_f32_e32 v44, v51, v57
	v_fma_f32 v39, -v52, v44, v39
	v_div_fmas_f32 v39, v39, v57, v44
	v_div_fixup_f32 v44, v39, v50, v58
	global_load_dwordx2 v[50:51], v[34:35], off offset:32
	global_load_dwordx2 v[52:53], v[34:35], off offset:48
	s_nop 0
	global_load_dwordx2 v[34:35], v[34:35], off offset:64
	v_pk_mul_f32 v[20:21], v[20:21], v[44:45]
	v_cvt_pk_bf16_f32 v44, v18, v19
	v_cvt_pk_bf16_f32 v45, v20, v21
	v_lshl_add_u64 v[18:19], v[48:49], 0, v[0:1]
	global_store_dwordx2 v[18:19], v[44:45], off offset:1024
	s_waitcnt vmcnt(4)
	v_lshlrev_b32_e32 v39, 16, v46
	v_and_b32_e32 v46, 0xffff0000, v46
	v_mul_f32_e32 v57, 0xbfb8aa3b, v39
	v_exp_f32_e32 v58, v57
	v_mul_f32_e32 v57, 0xbfb8aa3b, v46
	v_exp_f32_e32 v59, v57
	v_pk_mul_f32 v[22:23], v[22:23], v[38:39] op_sel_hi:[1,0]
	v_pk_add_f32 v[20:21], v[58:59], 1.0 op_sel_hi:[1,0]
	s_nop 0
	v_div_scale_f32 v57, s[52:53], v21, v21, v46
	v_rcp_f32_e32 v58, v57
	v_div_scale_f32 v48, s[52:53], v20, v20, v39
	v_rcp_f32_e32 v49, v48
	v_fma_f32 v0, -v57, v58, 1.0
	v_fmac_f32_e32 v58, v0, v58
	v_div_scale_f32 v0, vcc, v46, v21, v46
	v_mul_f32_e32 v44, v0, v58
	v_fma_f32 v45, -v57, v44, v0
	v_fmac_f32_e32 v44, v45, v58
	v_fma_f32 v0, -v57, v44, v0
	v_div_fmas_f32 v0, v0, v58, v44
	v_div_fixup_f32 v21, v0, v21, v46
	v_fma_f32 v0, -v48, v49, 1.0
	v_fmac_f32_e32 v49, v0, v49
	v_div_scale_f32 v0, vcc, v39, v20, v39
	v_mul_f32_e32 v46, v0, v49
	v_fma_f32 v44, -v48, v46, v0
	v_lshlrev_b32_e32 v57, 16, v47
	v_and_b32_e32 v47, 0xffff0000, v47
	v_fmac_f32_e32 v46, v44, v49
	v_mul_f32_e32 v44, 0xbfb8aa3b, v57
	v_mul_f32_e32 v45, 0xbfb8aa3b, v47
	v_exp_f32_e32 v44, v44
	v_exp_f32_e32 v45, v45
	v_fma_f32 v0, -v48, v46, v0
	v_div_fmas_f32 v0, v0, v49, v46
	v_div_fixup_f32 v20, v0, v20, v39
	v_pk_add_f32 v[44:45], v[44:45], 1.0 op_sel_hi:[1,0]
	v_pk_mul_f32 v[20:21], v[22:23], v[20:21]
	v_div_scale_f32 v46, s[52:53], v45, v45, v47
	v_rcp_f32_e32 v48, v46
	v_pk_mul_f32 v[22:23], v[24:25], v[38:39] op_sel_hi:[1,0]
	v_div_scale_f32 v39, s[52:53], v44, v44, v57
	v_fma_f32 v0, -v46, v48, 1.0
	v_fmac_f32_e32 v48, v0, v48
	v_div_scale_f32 v0, vcc, v47, v45, v47
	v_mul_f32_e32 v24, v0, v48
	v_fma_f32 v25, -v46, v24, v0
	v_fmac_f32_e32 v24, v25, v48
	v_fma_f32 v0, -v46, v24, v0
	v_rcp_f32_e32 v46, v39
	v_div_fmas_f32 v0, v0, v48, v24
	v_div_fixup_f32 v25, v0, v45, v47
	v_cvt_pk_bf16_f32 v20, v20, v21
	v_fma_f32 v0, -v39, v46, 1.0
	v_fmac_f32_e32 v46, v0, v46
	v_div_scale_f32 v0, vcc, v57, v44, v57
	v_mul_f32_e32 v24, v0, v46
	v_fma_f32 v45, -v39, v24, v0
	v_fmac_f32_e32 v24, v45, v46
	v_fma_f32 v0, -v39, v24, v0
	s_waitcnt vmcnt(3)
	v_lshlrev_b32_e32 v39, 16, v50
	v_div_fmas_f32 v0, v0, v46, v24
	v_and_b32_e32 v45, 0xffff0000, v50
	v_mul_f32_e32 v24, 0xbfb8aa3b, v39
	v_exp_f32_e32 v46, v24
	v_mul_f32_e32 v24, 0xbfb8aa3b, v45
	v_exp_f32_e32 v47, v24
	v_div_fixup_f32 v24, v0, v44, v57
	v_pk_mul_f32 v[22:23], v[22:23], v[24:25]
	v_pk_add_f32 v[24:25], v[46:47], 1.0 op_sel_hi:[1,0]
	s_nop 0
	v_div_scale_f32 v0, s[52:53], v25, v25, v45
	v_rcp_f32_e32 v44, v0
	v_cvt_pk_bf16_f32 v21, v22, v23
	global_store_dwordx2 v[18:19], v[20:21], off offset:1040
	v_pk_mul_f32 v[20:21], v[26:27], v[38:39] op_sel_hi:[1,0]
	v_fma_f32 v22, -v0, v44, 1.0
	v_fmac_f32_e32 v44, v22, v44
	v_div_scale_f32 v22, vcc, v45, v25, v45
	v_mul_f32_e32 v23, v22, v44
	v_fma_f32 v26, -v0, v23, v22
	v_fmac_f32_e32 v23, v26, v44
	v_fma_f32 v0, -v0, v23, v22
	v_div_scale_f32 v22, s[52:53], v24, v24, v39
	v_rcp_f32_e32 v46, v22
	v_div_fmas_f32 v0, v0, v44, v23
	v_div_fixup_f32 v23, v0, v25, v45
	v_lshlrev_b32_e32 v44, 16, v51
	v_fma_f32 v0, -v22, v46, 1.0
	v_fmac_f32_e32 v46, v0, v46
	v_div_scale_f32 v0, vcc, v39, v24, v39
	v_mul_f32_e32 v25, v0, v46
	v_fma_f32 v26, -v22, v25, v0
	v_and_b32_e32 v45, 0xffff0000, v51
	v_fmac_f32_e32 v25, v26, v46
	v_mul_f32_e32 v26, 0xbfb8aa3b, v44
	v_mul_f32_e32 v27, 0xbfb8aa3b, v45
	v_exp_f32_e32 v26, v26
	v_exp_f32_e32 v27, v27
	v_fma_f32 v0, -v22, v25, v0
	v_div_fmas_f32 v0, v0, v46, v25
	v_div_fixup_f32 v22, v0, v24, v39
	v_pk_add_f32 v[26:27], v[26:27], 1.0 op_sel_hi:[1,0]
	v_pk_mul_f32 v[20:21], v[20:21], v[22:23]
	v_div_scale_f32 v25, s[52:53], v27, v27, v45
	v_rcp_f32_e32 v46, v25
	v_pk_mul_f32 v[22:23], v[28:29], v[38:39] op_sel_hi:[1,0]
	s_waitcnt vmcnt(3)
	v_lshlrev_b32_e32 v39, 16, v52
	v_cvt_pk_bf16_f32 v20, v20, v21
	v_fma_f32 v0, -v25, v46, 1.0
	v_fmac_f32_e32 v46, v0, v46
	v_div_scale_f32 v0, vcc, v45, v27, v45
	v_mul_f32_e32 v24, v0, v46
	v_fma_f32 v28, -v25, v24, v0
	v_fmac_f32_e32 v24, v28, v46
	v_div_scale_f32 v28, s[52:53], v26, v26, v44
	v_rcp_f32_e32 v29, v28
	v_fma_f32 v0, -v25, v24, v0
	v_div_fmas_f32 v0, v0, v46, v24
	v_div_fixup_f32 v25, v0, v27, v45
	v_fma_f32 v0, -v28, v29, 1.0
	v_fmac_f32_e32 v29, v0, v29
	v_div_scale_f32 v0, vcc, v44, v26, v44
	v_mul_f32_e32 v24, v0, v29
	v_fma_f32 v27, -v28, v24, v0
	v_fmac_f32_e32 v24, v27, v29
	v_fma_f32 v0, -v28, v24, v0
	v_div_fmas_f32 v0, v0, v29, v24
	v_and_b32_e32 v27, 0xffff0000, v52
	v_mul_f32_e32 v24, 0xbfb8aa3b, v39
	v_exp_f32_e32 v28, v24
	v_mul_f32_e32 v24, 0xbfb8aa3b, v27
	v_exp_f32_e32 v29, v24
	v_div_fixup_f32 v24, v0, v26, v44
	v_pk_mul_f32 v[22:23], v[22:23], v[24:25]
	v_pk_mul_f32 v[2:3], v[2:3], v[38:39] op_sel_hi:[1,0]
	v_pk_add_f32 v[24:25], v[28:29], 1.0 op_sel_hi:[1,0]
	v_cvt_pk_bf16_f32 v21, v22, v23
	v_div_scale_f32 v0, s[52:53], v25, v25, v27
	v_rcp_f32_e32 v26, v0
	global_store_dwordx2 v[18:19], v[20:21], off offset:1056
	v_pk_mul_f32 v[20:21], v[30:31], v[38:39] op_sel_hi:[1,0]
	v_lshlrev_b32_e32 v30, 16, v53
	v_fma_f32 v22, -v0, v26, 1.0
	v_fmac_f32_e32 v26, v22, v26
	v_div_scale_f32 v22, vcc, v27, v25, v27
	v_mul_f32_e32 v23, v22, v26
	v_fma_f32 v28, -v0, v23, v22
	v_fmac_f32_e32 v23, v28, v26
	v_fma_f32 v0, -v0, v23, v22
	v_div_scale_f32 v22, s[52:53], v24, v24, v39
	v_rcp_f32_e32 v28, v22
	v_div_fmas_f32 v0, v0, v26, v23
	v_div_fixup_f32 v23, v0, v25, v27
	v_and_b32_e32 v29, 0xffff0000, v53
	v_fma_f32 v0, -v22, v28, 1.0
	v_fmac_f32_e32 v28, v0, v28
	v_div_scale_f32 v0, vcc, v39, v24, v39
	v_mul_f32_e32 v25, v0, v28
	v_fma_f32 v26, -v22, v25, v0
	v_fmac_f32_e32 v25, v26, v28
	v_mul_f32_e32 v26, 0xbfb8aa3b, v30
	v_mul_f32_e32 v27, 0xbfb8aa3b, v29
	v_exp_f32_e32 v26, v26
	v_exp_f32_e32 v27, v27
	v_fma_f32 v0, -v22, v25, v0
	v_div_fmas_f32 v0, v0, v28, v25
	v_div_fixup_f32 v22, v0, v24, v39
	v_pk_add_f32 v[26:27], v[26:27], 1.0 op_sel_hi:[1,0]
	v_pk_mul_f32 v[20:21], v[20:21], v[22:23]
	v_div_scale_f32 v25, s[52:53], v27, v27, v29
	v_rcp_f32_e32 v28, v25
	v_pk_mul_f32 v[22:23], v[32:33], v[38:39] op_sel_hi:[1,0]
	v_cvt_pk_bf16_f32 v20, v20, v21
	v_pk_mul_f32 v[4:5], v[4:5], v[38:39] op_sel_hi:[1,0]
	v_fma_f32 v0, -v25, v28, 1.0
	v_fmac_f32_e32 v28, v0, v28
	v_div_scale_f32 v0, vcc, v29, v27, v29
	v_mul_f32_e32 v24, v0, v28
	v_fma_f32 v31, -v25, v24, v0
	v_fmac_f32_e32 v24, v31, v28
	v_div_scale_f32 v31, s[52:53], v26, v26, v30
	v_rcp_f32_e32 v32, v31
	v_fma_f32 v0, -v25, v24, v0
	v_div_fmas_f32 v0, v0, v28, v24
	v_div_fixup_f32 v25, v0, v27, v29
	v_fma_f32 v0, -v31, v32, 1.0
	v_fmac_f32_e32 v32, v0, v32
	v_div_scale_f32 v0, vcc, v30, v26, v30
	v_mul_f32_e32 v24, v0, v32
	v_fma_f32 v27, -v31, v24, v0
	v_fmac_f32_e32 v24, v27, v32
	v_fma_f32 v0, -v31, v24, v0
	s_waitcnt vmcnt(3)
	v_lshlrev_b32_e32 v27, 16, v34
	v_div_fmas_f32 v0, v0, v32, v24
	v_and_b32_e32 v31, 0xffff0000, v34
	v_mul_f32_e32 v24, 0xbfb8aa3b, v27
	v_exp_f32_e32 v28, v24
	v_mul_f32_e32 v24, 0xbfb8aa3b, v31
	v_exp_f32_e32 v29, v24
	v_div_fixup_f32 v24, v0, v26, v30
	v_pk_mul_f32 v[22:23], v[22:23], v[24:25]
	v_pk_add_f32 v[24:25], v[28:29], 1.0 op_sel_hi:[1,0]
	s_nop 0
	v_div_scale_f32 v0, s[52:53], v25, v25, v31
	v_rcp_f32_e32 v26, v0
	v_cvt_pk_bf16_f32 v21, v22, v23
	global_store_dwordx2 v[18:19], v[20:21], off offset:1072
	v_and_b32_e32 v29, 0xffff0000, v35
	v_fma_f32 v20, -v0, v26, 1.0
	v_fmac_f32_e32 v26, v20, v26
	v_div_scale_f32 v20, vcc, v31, v25, v31
	v_mul_f32_e32 v21, v20, v26
	v_fma_f32 v22, -v0, v21, v20
	v_fmac_f32_e32 v21, v22, v26
	v_fma_f32 v0, -v0, v21, v20
	v_div_scale_f32 v20, s[52:53], v24, v24, v27
	v_rcp_f32_e32 v28, v20
	v_div_fmas_f32 v0, v0, v26, v21
	v_div_fixup_f32 v21, v0, v25, v31
	v_lshlrev_b32_e32 v26, 16, v35
	v_fma_f32 v0, -v20, v28, 1.0
	v_fmac_f32_e32 v28, v0, v28
	v_div_scale_f32 v0, vcc, v27, v24, v27
	v_mul_f32_e32 v25, v0, v28
	v_fma_f32 v22, -v20, v25, v0
	v_fmac_f32_e32 v25, v22, v28
	v_mul_f32_e32 v22, 0xbfb8aa3b, v26
	v_mul_f32_e32 v23, 0xbfb8aa3b, v29
	v_exp_f32_e32 v22, v22
	v_exp_f32_e32 v23, v23
	v_fma_f32 v0, -v20, v25, v0
	v_div_fmas_f32 v0, v0, v28, v25
	v_div_fixup_f32 v20, v0, v24, v27
	v_pk_add_f32 v[22:23], v[22:23], 1.0 op_sel_hi:[1,0]
	v_pk_mul_f32 v[2:3], v[2:3], v[20:21]
	v_div_scale_f32 v25, s[52:53], v23, v23, v29
	v_rcp_f32_e32 v28, v25
	v_div_scale_f32 v24, s[52:53], v22, v22, v26
	v_and_b32_e32 v27, 0xffff0000, v36
	v_fma_f32 v0, -v25, v28, 1.0
	v_fmac_f32_e32 v28, v0, v28
	v_div_scale_f32 v0, vcc, v29, v23, v29
	v_mul_f32_e32 v20, v0, v28
	v_fma_f32 v21, -v25, v20, v0
	v_fmac_f32_e32 v20, v21, v28
	v_fma_f32 v0, -v25, v20, v0
	v_rcp_f32_e32 v25, v24
	v_div_fmas_f32 v0, v0, v28, v20
	v_div_fixup_f32 v21, v0, v23, v29
	v_cvt_pk_bf16_f32 v2, v2, v3
	v_fma_f32 v0, -v24, v25, 1.0
	v_fmac_f32_e32 v25, v0, v25
	v_div_scale_f32 v0, vcc, v26, v22, v26
	v_mul_f32_e32 v20, v0, v25
	v_fma_f32 v23, -v24, v20, v0
	v_fmac_f32_e32 v20, v23, v25
	v_fma_f32 v0, -v24, v20, v0
	v_lshlrev_b32_e32 v23, 16, v36
	v_div_fmas_f32 v0, v0, v25, v20
	v_mul_f32_e32 v20, 0xbfb8aa3b, v23
	v_exp_f32_e32 v24, v20
	v_mul_f32_e32 v20, 0xbfb8aa3b, v27
	v_exp_f32_e32 v25, v20
	v_div_fixup_f32 v20, v0, v22, v26
	v_pk_mul_f32 v[4:5], v[4:5], v[20:21]
	v_pk_add_f32 v[20:21], v[24:25], 1.0 op_sel_hi:[1,0]
	s_nop 0
	v_div_scale_f32 v0, s[52:53], v21, v21, v27
	v_rcp_f32_e32 v22, v0
	v_cvt_pk_bf16_f32 v3, v4, v5
	global_store_dwordx2 v[18:19], v[2:3], off offset:1088
	v_pk_mul_f32 v[2:3], v[6:7], v[38:39] op_sel_hi:[1,0]
	v_fma_f32 v4, -v0, v22, 1.0
	v_fmac_f32_e32 v22, v4, v22
	v_div_scale_f32 v4, vcc, v27, v21, v27
	v_mul_f32_e32 v5, v4, v22
	v_fma_f32 v6, -v0, v5, v4
	v_fmac_f32_e32 v5, v6, v22
	v_fma_f32 v0, -v0, v5, v4
	v_div_scale_f32 v4, s[52:53], v20, v20, v23
	v_rcp_f32_e32 v24, v4
	v_div_fmas_f32 v0, v0, v22, v5
	v_div_fixup_f32 v5, v0, v21, v27
	v_lshlrev_b32_e32 v22, 16, v37
	v_fma_f32 v0, -v4, v24, 1.0
	v_fmac_f32_e32 v24, v0, v24
	v_div_scale_f32 v0, vcc, v23, v20, v23
	v_mul_f32_e32 v21, v0, v24
	v_fma_f32 v6, -v4, v21, v0
	v_and_b32_e32 v25, 0xffff0000, v37
	v_fmac_f32_e32 v21, v6, v24
	v_mul_f32_e32 v6, 0xbfb8aa3b, v22
	v_mul_f32_e32 v7, 0xbfb8aa3b, v25
	v_exp_f32_e32 v6, v6
	v_exp_f32_e32 v7, v7
	v_fma_f32 v0, -v4, v21, v0
	v_div_fmas_f32 v0, v0, v24, v21
	v_div_fixup_f32 v4, v0, v20, v23
	v_pk_add_f32 v[6:7], v[6:7], 1.0 op_sel_hi:[1,0]
	v_pk_mul_f32 v[2:3], v[2:3], v[4:5]
	v_div_scale_f32 v21, s[52:53], v7, v7, v25
	v_rcp_f32_e32 v24, v21
	v_pk_mul_f32 v[4:5], v[8:9], v[38:39] op_sel_hi:[1,0]
	v_cvt_pk_bf16_f32 v2, v2, v3
	v_fma_f32 v0, -v21, v24, 1.0
	v_fmac_f32_e32 v24, v0, v24
	v_div_scale_f32 v0, vcc, v25, v7, v25
	v_mul_f32_e32 v8, v0, v24
	v_fma_f32 v9, -v21, v8, v0
	v_fmac_f32_e32 v8, v9, v24
	v_div_scale_f32 v9, s[52:53], v6, v6, v22
	v_rcp_f32_e32 v20, v9
	v_fma_f32 v0, -v21, v8, v0
	v_div_fmas_f32 v0, v0, v24, v8
	v_div_fixup_f32 v7, v0, v7, v25
	v_fma_f32 v0, -v9, v20, 1.0
	v_fmac_f32_e32 v20, v0, v20
	v_div_scale_f32 v0, vcc, v22, v6, v22
	v_mul_f32_e32 v8, v0, v20
	v_fma_f32 v21, -v9, v8, v0
	v_fmac_f32_e32 v8, v21, v20
	v_fma_f32 v0, -v9, v8, v0
	v_div_fmas_f32 v0, v0, v20, v8
	v_lshlrev_b32_e32 v20, 16, v40
	v_and_b32_e32 v21, 0xffff0000, v40
	v_mul_f32_e32 v8, 0xbfb8aa3b, v20
	v_mul_f32_e32 v9, 0xbfb8aa3b, v21
	v_exp_f32_e32 v8, v8
	v_exp_f32_e32 v9, v9
	v_div_fixup_f32 v6, v0, v6, v22
	v_pk_mul_f32 v[4:5], v[4:5], v[6:7]
	v_pk_add_f32 v[6:7], v[8:9], 1.0 op_sel_hi:[1,0]
	s_nop 0
	v_div_scale_f32 v0, s[52:53], v7, v7, v21
	v_rcp_f32_e32 v8, v0
	v_cvt_pk_bf16_f32 v3, v4, v5
	global_store_dwordx2 v[18:19], v[2:3], off offset:1104
	v_pk_mul_f32 v[2:3], v[10:11], v[38:39] op_sel_hi:[1,0]
	v_fma_f32 v4, -v0, v8, 1.0
	v_fmac_f32_e32 v8, v4, v8
	v_div_scale_f32 v4, vcc, v21, v7, v21
	v_mul_f32_e32 v5, v4, v8
	v_fma_f32 v9, -v0, v5, v4
	v_fmac_f32_e32 v5, v9, v8
	v_fma_f32 v0, -v0, v5, v4
	v_div_scale_f32 v4, s[52:53], v6, v6, v20
	v_rcp_f32_e32 v10, v4
	v_div_fmas_f32 v0, v0, v8, v5
	v_div_fixup_f32 v5, v0, v7, v21
	v_lshlrev_b32_e32 v21, 16, v41
	v_fma_f32 v0, -v4, v10, 1.0
	v_fmac_f32_e32 v10, v0, v10
	v_div_scale_f32 v0, vcc, v20, v6, v20
	v_mul_f32_e32 v7, v0, v10
	v_fma_f32 v8, -v4, v7, v0
	v_and_b32_e32 v11, 0xffff0000, v41
	v_fmac_f32_e32 v7, v8, v10
	v_mul_f32_e32 v8, 0xbfb8aa3b, v21
	v_mul_f32_e32 v9, 0xbfb8aa3b, v11
	v_exp_f32_e32 v8, v8
	v_exp_f32_e32 v9, v9
	v_fma_f32 v0, -v4, v7, v0
	v_div_fmas_f32 v0, v0, v10, v7
	v_div_fixup_f32 v4, v0, v6, v20
	v_pk_add_f32 v[8:9], v[8:9], 1.0 op_sel_hi:[1,0]
	v_pk_mul_f32 v[2:3], v[2:3], v[4:5]
	v_div_scale_f32 v7, s[52:53], v9, v9, v11
	v_rcp_f32_e32 v10, v7
	v_pk_mul_f32 v[4:5], v[12:13], v[38:39] op_sel_hi:[1,0]
	v_cvt_pk_bf16_f32 v2, v2, v3
	v_fma_f32 v0, -v7, v10, 1.0
	v_fmac_f32_e32 v10, v0, v10
	v_div_scale_f32 v0, vcc, v11, v9, v11
	v_mul_f32_e32 v6, v0, v10
	v_fma_f32 v12, -v7, v6, v0
	v_fmac_f32_e32 v6, v12, v10
	v_div_scale_f32 v12, s[52:53], v8, v8, v21
	v_rcp_f32_e32 v13, v12
	v_fma_f32 v0, -v7, v6, v0
	v_div_fmas_f32 v0, v0, v10, v6
	v_div_fixup_f32 v7, v0, v9, v11
	v_fma_f32 v0, -v12, v13, 1.0
	v_fmac_f32_e32 v13, v0, v13
	v_div_scale_f32 v0, vcc, v21, v8, v21
	v_mul_f32_e32 v6, v0, v13
	v_fma_f32 v9, -v12, v6, v0
	v_fmac_f32_e32 v6, v9, v13
	v_fma_f32 v0, -v12, v6, v0
	v_and_b32_e32 v9, 0xffff0000, v42
	v_div_fmas_f32 v0, v0, v13, v6
	v_lshlrev_b32_e32 v12, 16, v42
	v_mul_f32_e32 v6, 0xbfb8aa3b, v9
	v_exp_f32_e32 v11, v6
	v_mul_f32_e32 v6, 0xbfb8aa3b, v12
	v_exp_f32_e32 v10, v6
	v_div_fixup_f32 v6, v0, v8, v21
	v_pk_mul_f32 v[4:5], v[4:5], v[6:7]
	v_and_b32_e32 v13, 0xffff0000, v43
	v_pk_add_f32 v[6:7], v[10:11], 1.0 op_sel_hi:[1,0]
	v_cvt_pk_bf16_f32 v3, v4, v5
	v_div_scale_f32 v0, s[52:53], v7, v7, v9
	v_rcp_f32_e32 v8, v0
	v_lshlrev_b32_e32 v11, 16, v43
	global_store_dwordx2 v[18:19], v[2:3], off offset:1120
	v_pk_mul_f32 v[2:3], v[14:15], v[38:39] op_sel_hi:[1,0]
	v_fma_f32 v4, -v0, v8, 1.0
	v_fmac_f32_e32 v8, v4, v8
	v_div_scale_f32 v4, vcc, v9, v7, v9
	v_mul_f32_e32 v5, v4, v8
	v_fma_f32 v10, -v0, v5, v4
	v_fmac_f32_e32 v5, v10, v8
	v_fma_f32 v0, -v0, v5, v4
	v_div_scale_f32 v4, s[52:53], v6, v6, v12
	v_rcp_f32_e32 v10, v4
	v_div_fmas_f32 v0, v0, v8, v5
	v_div_fixup_f32 v5, v0, v7, v9
	v_mul_f32_e32 v9, 0xbfb8aa3b, v13
	v_fma_f32 v0, -v4, v10, 1.0
	v_fmac_f32_e32 v10, v0, v10
	v_div_scale_f32 v0, vcc, v12, v6, v12
	v_mul_f32_e32 v7, v0, v10
	v_fma_f32 v8, -v4, v7, v0
	v_fmac_f32_e32 v7, v8, v10
	v_mul_f32_e32 v8, 0xbfb8aa3b, v11
	v_exp_f32_e32 v8, v8
	v_exp_f32_e32 v9, v9
	v_fma_f32 v0, -v4, v7, v0
	v_div_fmas_f32 v0, v0, v10, v7
	v_div_fixup_f32 v4, v0, v6, v12
	v_pk_add_f32 v[8:9], v[8:9], 1.0 op_sel_hi:[1,0]
	v_pk_mul_f32 v[2:3], v[2:3], v[4:5]
	v_div_scale_f32 v7, s[52:53], v9, v9, v13
	v_rcp_f32_e32 v10, v7
	v_pk_mul_f32 v[4:5], v[16:17], v[38:39] op_sel_hi:[1,0]
	v_cvt_pk_bf16_f32 v2, v2, v3
	v_fma_f32 v0, -v7, v10, 1.0
	v_fmac_f32_e32 v10, v0, v10
	v_div_scale_f32 v0, vcc, v13, v9, v13
	v_mul_f32_e32 v6, v0, v10
	v_fma_f32 v12, -v7, v6, v0
	v_fmac_f32_e32 v6, v12, v10
	v_div_scale_f32 v12, s[52:53], v8, v8, v11
	v_rcp_f32_e32 v14, v12
	v_fma_f32 v0, -v7, v6, v0
	v_div_fmas_f32 v0, v0, v10, v6
	v_div_fixup_f32 v7, v0, v9, v13
	v_fma_f32 v0, -v12, v14, 1.0
	v_fmac_f32_e32 v14, v0, v14
	v_div_scale_f32 v0, vcc, v11, v8, v11
	v_mul_f32_e32 v6, v0, v14
	v_fma_f32 v9, -v12, v6, v0
	v_fmac_f32_e32 v6, v9, v14
	v_fma_f32 v0, -v12, v6, v0
	v_div_fmas_f32 v0, v0, v14, v6
	v_div_fixup_f32 v6, v0, v8, v11
	v_pk_mul_f32 v[4:5], v[4:5], v[6:7]
	s_nop 0
	v_cvt_pk_bf16_f32 v3, v4, v5
	global_store_dwordx2 v[18:19], v[2:3], off offset:1136
	s_and_saveexec_b64 s[52:53], s[0:1]
	s_cbranch_execz .LBB0_422

	.amdhsa_kernel _Z8fwd_mega4Args
		.amdhsa_group_segment_fixed_size 0
		.amdhsa_private_segment_fixed_size 0
		.amdhsa_kernarg_size 344
		.amdhsa_user_sgpr_count 2
		.amdhsa_user_sgpr_dispatch_ptr 0
		.amdhsa_user_sgpr_queue_ptr 0
		.amdhsa_user_sgpr_kernarg_segment_ptr 1
		.amdhsa_user_sgpr_dispatch_id 0
		.amdhsa_user_sgpr_kernarg_preload_length 0
		.amdhsa_user_sgpr_kernarg_preload_offset 0
		.amdhsa_user_sgpr_private_segment_size 0
		.amdhsa_uses_dynamic_stack 0
		.amdhsa_enable_private_segment 0
		.amdhsa_system_sgpr_workgroup_id_x 1
		.amdhsa_system_sgpr_workgroup_id_y 0
		.amdhsa_system_sgpr_workgroup_id_z 0
		.amdhsa_system_sgpr_workgroup_info 0
		.amdhsa_system_vgpr_workitem_id 2
		.amdhsa_next_free_vgpr 256
		.amdhsa_next_free_sgpr 102
		.amdhsa_accum_offset 256
		.amdhsa_reserve_vcc 1
		.amdhsa_float_round_mode_32 0
		.amdhsa_float_round_mode_16_64 0
		.amdhsa_float_denorm_mode_32 3
		.amdhsa_float_denorm_mode_16_64 3
		.amdhsa_dx10_clamp 1
		.amdhsa_ieee_mode 1
		.amdhsa_fp16_overflow 0
		.amdhsa_tg_split 0
		.amdhsa_exception_fp_ieee_invalid_op 0
		.amdhsa_exception_fp_denorm_src 0
		.amdhsa_exception_fp_ieee_div_zero 0
		.amdhsa_exception_fp_ieee_overflow 0
		.amdhsa_exception_fp_ieee_underflow 0
		.amdhsa_exception_fp_ieee_inexact 0
		.amdhsa_exception_int_div_zero 0
	.end_amdhsa_kernel

.Lfunc_end0:
	.size	_Z8fwd_mega4Args, .Lfunc_end0-_Z8fwd_mega4Args
	.set _Z8fwd_mega4Args.num_vgpr, 256
	.set _Z8fwd_mega4Args.num_agpr, 0
	.set _Z8fwd_mega4Args.numbered_sgpr, 100
	.set _Z8fwd_mega4Args.num_named_barrier, 0
	.set _Z8fwd_mega4Args.private_seg_size, 0
	.set _Z8fwd_mega4Args.uses_vcc, 1
	.set _Z8fwd_mega4Args.uses_flat_scratch, 0
	.set _Z8fwd_mega4Args.has_dyn_sized_stack, 0
	.set _Z8fwd_mega4Args.has_recursion, 0
	.set _Z8fwd_mega4Args.has_indirect_call, 0

amdhsa.kernels:
  - .agpr_count:     0
    .args:
      - .offset:         0
        .size:           88
        .value_kind:     by_value
      - .offset:         88
        .size:           4
        .value_kind:     hidden_block_count_x
      - .offset:         92
        .size:           4
        .value_kind:     hidden_block_count_y
      - .offset:         96
        .size:           4
        .value_kind:     hidden_block_count_z
      - .offset:         100
        .size:           2
        .value_kind:     hidden_group_size_x
      - .offset:         102
        .size:           2
        .value_kind:     hidden_group_size_y
      - .offset:         104
        .size:           2
        .value_kind:     hidden_group_size_z
      - .offset:         106
        .size:           2
        .value_kind:     hidden_remainder_x
      - .offset:         108
        .size:           2
        .value_kind:     hidden_remainder_y
      - .offset:         110
        .size:           2
        .value_kind:     hidden_remainder_z
      - .offset:         128
        .size:           8
        .value_kind:     hidden_global_offset_x
      - .offset:         136
        .size:           8
        .value_kind:     hidden_global_offset_y
      - .offset:         144
        .size:           8
        .value_kind:     hidden_global_offset_z
      - .offset:         152
        .size:           2
        .value_kind:     hidden_grid_dims
      - .offset:         176
        .size:           8
        .value_kind:     hidden_multigrid_sync_arg
      - .offset:         208
        .size:           4
        .value_kind:     hidden_dynamic_lds_size
    .group_segment_fixed_size: 0
    .kernarg_segment_align: 8
    .kernarg_segment_size: 344
    .language:       OpenCL C
    .language_version:
      - 2
      - 0
    .max_flat_workgroup_size: 512
    .name:           _Z8fwd_mega4Args
    .private_segment_fixed_size: 0
    .sgpr_count:     108
    .sgpr_spill_count: 1
    .symbol:         _Z8fwd_mega4Args.kd
    .uniform_work_group_size: 1
    .uses_dynamic_stack: false
    .vgpr_count:     256
    .vgpr_spill_count: 0
    .wavefront_size: 64
